# B1 prep item: token-shifted LoRA input columns with all 8 loads in flight instead of 8 serialized round trips
# speedup vs baseline: 1.0080x; 1.0016x over previous
.LBB0_405:
	s_andn2_saveexec_b64 s[56:57], s[96:97]
	s_cbranch_execz .LBB0_497
	v_mov_b32_e32 v130, v133
	v_readlane_b32 s0, v214, 12
	v_lshlrev_b32_e32 v132, 4, v206
	v_and_b32_e32 v98, 15, v130
	v_readlane_b32 s1, v214, 13
	v_or_b32_e32 v134, v98, v132
	v_and_b32_e32 v150, 0xffffffc0, v130
	s_waitcnt lgkmcnt(0)
	v_mov_b64_e32 v[4:5], s[0:1]
	v_bfe_u32 v207, v130, 4, 2
	v_mad_i64_i32 v[0:1], s[0:1], v134, s83, v[4:5]
	v_ashrrev_i32_e32 v151, 31, v150
	v_lshl_add_u64 v[2:3], v[150:151], 1, v[0:1]
	v_lshlrev_b32_e32 v0, 3, v207
	v_mov_b32_e32 v1, v65
	v_lshl_add_u64 v[2:3], v[2:3], 0, v[0:1]
	global_load_dwordx2 v[146:147], v[2:3], off offset:1024
	global_load_dwordx2 v[144:145], v[2:3], off offset:1056
	global_load_dwordx2 v[142:143], v[2:3], off offset:1088
	global_load_dwordx2 v[140:141], v[2:3], off offset:1120
	global_load_dwordx2 v[72:73], v[2:3], off offset:2048
	global_load_dwordx2 v[94:95], v[2:3], off offset:2080
	global_load_dwordx2 v[120:121], v[2:3], off offset:2112
	global_load_dwordx2 v[138:139], v[2:3], off offset:2144
	global_load_dwordx2 v[70:71], v[2:3], off offset:3072
	global_load_dwordx2 v[96:97], v[2:3], off offset:3104
	global_load_dwordx2 v[118:119], v[2:3], off offset:3136
	global_load_dwordx2 v[136:137], v[2:3], off offset:3168
	v_and_b32_e32 v2, 0x7f, v130
	v_lshlrev_b32_e32 v64, 2, v2
	v_lshl_add_u64 v[6:7], s[74:75], 0, v[64:65]
	v_add_co_u32_e32 v6, vcc, s73, v6
	s_nop 1
	v_addc_co_u32_e32 v7, vcc, 0, v7, vcc
	s_barrier
	global_load_dword v3, v[6:7], off offset:2048
	v_and_b32_e32 v1, 0x7f, v206
	v_add_u32_e32 v131, 0x200, v130
	s_movk_i32 s0, 0x400
	v_cmp_gt_i32_e64 s[42:43], s0, v206
	s_movk_i32 s0, 0x3ff
	v_cmp_lt_i32_e64 s[40:41], s0, v206
	v_cmp_eq_u32_e64 s[44:45], 0, v1
	v_readlane_b32 s20, v214, 12
	v_readlane_b32 s21, v214, 13
	v_lshlrev_b32_e32 v4, 1, v2
	v_ashrrev_i32_e32 v6, 7, v130
	v_add_u32_e32 v8, v6, v132
	s_movk_i32 s2, 0x1000
	v_add_u32_e32 v9, 4, v8
	v_add_u32_e32 v10, 8, v8
	v_add_u32_e32 v11, 12, v8
	v_mul_lo_u32 v12, v8, s83
	v_add3_u32 v12, v12, v4, s2
	global_load_ushort v16, v12, s[20:21]
	v_mul_lo_u32 v13, v9, s83
	v_add3_u32 v13, v13, v4, s2
	global_load_ushort v17, v13, s[20:21]
	v_mul_lo_u32 v14, v10, s83
	v_add3_u32 v14, v14, v4, s2
	global_load_ushort v18, v14, s[20:21]
	v_mul_lo_u32 v15, v11, s83
	v_add3_u32 v15, v15, v4, s2
	global_load_ushort v19, v15, s[20:21]
	s_and_b64 vcc, exec, s[40:41]
	s_cbranch_vccz .Lpc_prompt
	s_movk_i32 s2, 0x1800
	v_add_u32_e32 v20, 0xffffc000, v8
	v_mul_lo_u32 v20, v20, s86
	v_add3_u32 v20, v20, v64, s2
	global_load_dword v24, v20, s[64:65]
	v_add_u32_e32 v21, 0xffffc000, v9
	v_mul_lo_u32 v21, v21, s86
	v_add3_u32 v21, v21, v64, s2
	global_load_dword v25, v21, s[64:65]
	v_add_u32_e32 v22, 0xffffc000, v10
	v_mul_lo_u32 v22, v22, s86
	v_add3_u32 v22, v22, v64, s2
	global_load_dword v26, v22, s[64:65]
	v_add_u32_e32 v23, 0xffffc000, v11
	v_mul_lo_u32 v23, v23, s86
	v_add3_u32 v23, v23, v64, s2
	global_load_dword v27, v23, s[64:65]
	s_waitcnt vmcnt(0)
	s_branch .Lpc_join
.Lpc_prompt:
	v_cmp_gt_u32_e32 vcc, 0x80, v130
	s_and_b64 s[22:23], vcc, s[44:45]
	v_add_u32_e32 v20, -1, v8
	v_cndmask_b32_e64 v20, v20, v8, s[22:23]
	v_add_u32_e32 v21, -1, v9
	v_add_u32_e32 v22, -1, v10
	v_add_u32_e32 v23, -1, v11
	v_mul_lo_u32 v20, v20, s83
	v_add3_u32 v20, v20, v4, s2
	global_load_ushort v24, v20, s[20:21]
	v_mul_lo_u32 v21, v21, s83
	v_add3_u32 v21, v21, v4, s2
	global_load_ushort v25, v21, s[20:21]
	v_mul_lo_u32 v22, v22, s83
	v_add3_u32 v22, v22, v4, s2
	global_load_ushort v26, v22, s[20:21]
	v_mul_lo_u32 v23, v23, s83
	v_add3_u32 v23, v23, v4, s2
	global_load_ushort v27, v23, s[20:21]
	s_waitcnt vmcnt(0)
	v_lshlrev_b32_e32 v24, 16, v24
	v_lshlrev_b32_e32 v25, 16, v25
	v_lshlrev_b32_e32 v26, 16, v26
	v_lshlrev_b32_e32 v27, 16, v27
	v_cndmask_b32_e64 v24, v24, 0, s[22:23]
.Lpc_join:
	v_lshlrev_b32_e32 v16, 16, v16
	v_lshlrev_b32_e32 v17, 16, v17
	v_lshlrev_b32_e32 v18, 16, v18
	v_lshlrev_b32_e32 v19, 16, v19
	v_sub_f32_e32 v24, v24, v16
	v_sub_f32_e32 v25, v25, v17
	v_sub_f32_e32 v26, v26, v18
	v_sub_f32_e32 v27, v27, v19
	v_fmac_f32_e32 v16, v3, v24
	v_fmac_f32_e32 v17, v3, v25
	v_fmac_f32_e32 v18, v3, v26
	v_fmac_f32_e32 v19, v3, v27
	v_mul_u32_u24_e32 v28, 0x90, v6
	v_add_u32_e32 v28, v28, v4
	v_readfirstlane_b32 s0, v130
	s_bitcmp1_b32 s0, 6
	s_cbranch_scc1 .Lpc_ad
	v_add_f32_e32 v5, v16, v16
	v_mul_f32_e32 v5, 0x3fb8aa3b, v5
	v_exp_f32_e32 v5, v5
	s_nop 0
	v_add_f32_e32 v5, 1.0, v5
	v_div_scale_f32 v7, s[22:23], v5, v5, 2.0
	v_rcp_f32_e32 v29, v7
	v_div_scale_f32 v9, vcc, 2.0, v5, 2.0
	v_fma_f32 v10, -v7, v29, 1.0
	v_fmac_f32_e32 v29, v10, v29
	v_mul_f32_e32 v10, v9, v29
	v_fma_f32 v11, -v7, v10, v9
	v_fmac_f32_e32 v10, v11, v29
	v_fma_f32 v7, -v7, v10, v9
	v_div_fmas_f32 v7, v7, v29, v10
	v_div_fixup_f32 v5, v7, v5, 2.0
	v_sub_f32_e32 v5, 1.0, v5
	v_bfe_u32 v7, v5, 16, 1
	v_add3_u32 v5, v5, v7, s27
	ds_write_b16_d16_hi v28, v5 offset:0
	v_add_f32_e32 v5, v17, v17
	v_mul_f32_e32 v5, 0x3fb8aa3b, v5
	v_exp_f32_e32 v5, v5
	s_nop 0
	v_add_f32_e32 v5, 1.0, v5
	v_div_scale_f32 v7, s[22:23], v5, v5, 2.0
	v_rcp_f32_e32 v29, v7
	v_div_scale_f32 v9, vcc, 2.0, v5, 2.0
	v_fma_f32 v10, -v7, v29, 1.0
	v_fmac_f32_e32 v29, v10, v29
	v_mul_f32_e32 v10, v9, v29
	v_fma_f32 v11, -v7, v10, v9
	v_fmac_f32_e32 v10, v11, v29
	v_fma_f32 v7, -v7, v10, v9
	v_div_fmas_f32 v7, v7, v29, v10
	v_div_fixup_f32 v5, v7, v5, 2.0
	v_sub_f32_e32 v5, 1.0, v5
	v_bfe_u32 v7, v5, 16, 1
	v_add3_u32 v5, v5, v7, s27
	ds_write_b16_d16_hi v28, v5 offset:576
	v_add_f32_e32 v5, v18, v18
	v_mul_f32_e32 v5, 0x3fb8aa3b, v5
	v_exp_f32_e32 v5, v5
	s_nop 0
	v_add_f32_e32 v5, 1.0, v5
	v_div_scale_f32 v7, s[22:23], v5, v5, 2.0
	v_rcp_f32_e32 v29, v7
	v_div_scale_f32 v9, vcc, 2.0, v5, 2.0
	v_fma_f32 v10, -v7, v29, 1.0
	v_fmac_f32_e32 v29, v10, v29
	v_mul_f32_e32 v10, v9, v29
	v_fma_f32 v11, -v7, v10, v9
	v_fmac_f32_e32 v10, v11, v29
	v_fma_f32 v7, -v7, v10, v9
	v_div_fmas_f32 v7, v7, v29, v10
	v_div_fixup_f32 v5, v7, v5, 2.0
	v_sub_f32_e32 v5, 1.0, v5
	v_bfe_u32 v7, v5, 16, 1
	v_add3_u32 v5, v5, v7, s27
	ds_write_b16_d16_hi v28, v5 offset:1152
	v_add_f32_e32 v5, v19, v19
	v_mul_f32_e32 v5, 0x3fb8aa3b, v5
	v_exp_f32_e32 v5, v5
	s_nop 0
	v_add_f32_e32 v5, 1.0, v5
	v_div_scale_f32 v7, s[22:23], v5, v5, 2.0
	v_rcp_f32_e32 v29, v7
	v_div_scale_f32 v9, vcc, 2.0, v5, 2.0
	v_fma_f32 v10, -v7, v29, 1.0
	v_fmac_f32_e32 v29, v10, v29
	v_mul_f32_e32 v10, v9, v29
	v_fma_f32 v11, -v7, v10, v9
	v_fmac_f32_e32 v10, v11, v29
	v_fma_f32 v7, -v7, v10, v9
	v_div_fmas_f32 v7, v7, v29, v10
	v_div_fixup_f32 v5, v7, v5, 2.0
	v_sub_f32_e32 v5, 1.0, v5
	v_bfe_u32 v7, v5, 16, 1
	v_add3_u32 v5, v5, v7, s27
	ds_write_b16_d16_hi v28, v5 offset:1728
	s_branch .Lpc_done
.Lpc_ad:
	v_bfe_u32 v5, v16, 16, 1
	v_add3_u32 v5, v16, v5, s27
	ds_write_b16_d16_hi v28, v5 offset:2176
	v_bfe_u32 v5, v17, 16, 1
	v_add3_u32 v5, v17, v5, s27
	ds_write_b16_d16_hi v28, v5 offset:2752
	v_bfe_u32 v5, v18, 16, 1
	v_add3_u32 v5, v18, v5, s27
	ds_write_b16_d16_hi v28, v5 offset:3328
	v_bfe_u32 v5, v19, 16, 1
	v_add3_u32 v5, v19, v5, s27
	ds_write_b16_d16_hi v28, v5 offset:3904
.Lpc_done:
	v_mul_u32_u24_e32 v2, 0x48, v98
	v_lshlrev_b32_e32 v2, 1, v2
	v_lshlrev_b32_e32 v3, 4, v207
	v_add3_u32 v2, 0, v2, v3
	s_waitcnt lgkmcnt(0)
	s_barrier
	ds_read_b128 v[32:35], v2
	ds_read_b128 v[24:27], v2 offset:64
	ds_read_b128 v[28:31], v2 offset:2304
	ds_read_b128 v[20:23], v2 offset:2368
	v_ashrrev_i32_e32 v148, 6, v130
	s_movk_i32 s0, 0x3fff
	v_ashrrev_i32_e32 v135, 31, v134
	v_cmp_lt_i32_e32 vcc, s0, v134
	v_ashrrev_i32_e32 v149, 31, v148
	s_and_saveexec_b64 s[0:1], vcc
	s_xor_b64 s[0:1], exec, s[0:1]
	v_lshl_add_u64 v[78:79], v[134:135], 3, v[148:149]
	s_andn2_saveexec_b64 s[0:1], s[0:1]
	v_ashrrev_i32_e32 v2, 8, v132
	v_and_b32_e32 v2, -8, v2
	v_add_u32_e32 v2, v148, v2
	v_ashrrev_i32_e32 v3, 31, v2
	v_lshlrev_b64 v[78:79], 11, v[2:3]
	s_movk_i32 s2, 0x7ff
	v_and_or_b32 v78, v134, s2, v78
	s_or_b64 exec, exec, s[0:1]
	v_lshlrev_b32_e32 v6, 1, v0
	v_mov_b32_e32 v7, v65
	v_lshl_add_u64 v[160:161], v[126:127], 0, v[6:7]
	v_lshlrev_b32_e32 v8, 7, v98
	v_mov_b32_e32 v9, v65
	v_lshl_add_u64 v[74:75], v[160:161], 0, v[8:9]
	global_load_dwordx4 v[2:5], v[74:75], off
	v_lshl_add_u64 v[162:163], v[128:129], 0, v[6:7]
	v_lshl_add_u64 v[76:77], v[162:163], 0, v[8:9]
	global_load_dwordx4 v[6:9], v[76:77], off
	global_load_dwordx4 v[12:15], v[74:75], off offset:64
	global_load_dwordx4 v[16:19], v[76:77], off offset:64
	v_lshlrev_b32_e32 v64, 2, v207
	v_or_b32_e32 v10, v98, v1
	v_add_u32_e32 v11, 0xffffc000, v134
	v_mov_b64_e32 v[0:1], s[64:65]
	v_lshl_add_u32 v208, v64, 2, v204
	v_cmp_ne_u32_e64 s[0:1], 0, v10
	v_mad_i64_i32 v[158:159], s[20:21], v11, s86, v[0:1]
	v_or_b32_e32 v80, v64, v150
	s_waitcnt vmcnt(2) lgkmcnt(1)
	v_mfma_f32_16x16x32_bf16 v[52:55], v[6:9], v[28:31], 0
	v_mfma_f32_16x16x32_bf16 v[36:39], v[2:5], v[32:35], 0
	ds_read_b128 v[0:3], v208 offset:8192
	ds_read_b128 v[48:51], v208 offset:8448
	ds_read_b128 v[8:11], v208 offset:8704
	ds_read_b128 v[40:43], v208 offset:8960
	s_waitcnt vmcnt(1)
	v_mfma_f32_16x16x32_bf16 v[66:69], v[12:15], v[24:27], v[36:39]
	ds_read_b128 v[4:7], v208 offset:9216
	ds_read_b128 v[12:15], v208 offset:9472
	ds_read_b128 v[44:47], v208 offset:9728
	ds_read_b128 v[36:39], v208 offset:9984
	s_waitcnt vmcnt(0) lgkmcnt(8)
	v_mfma_f32_16x16x32_bf16 v[52:55], v[16:19], v[20:23], v[52:55]
	s_and_saveexec_b64 s[20:21], s[40:41]
	s_xor_b64 s[20:21], exec, s[20:21]
	s_cbranch_execz .LBB0_452
	v_ashrrev_i32_e32 v81, 31, v80
	v_lshl_add_u64 v[60:61], v[80:81], 2, v[158:159]
	global_load_dwordx4 v[16:19], v[60:61], off
	global_load_dwordx4 v[56:59], v[60:61], off offset:2048
	v_add_co_u32_e32 v60, vcc, 0x1000, v60
	s_nop 1
	v_addc_co_u32_e32 v61, vcc, 0, v61, vcc
	global_load_dwordx4 v[60:63], v[60:61], off
